# mixer A: loop-top wait covers only the 10 prefetch loads (vmcnt(5)); output stores of the previous unit stay in flight
# speedup vs baseline: 1.0088x; 1.0010x over previous
; #define LAS __attribute__((address_space(3)))
; __device__ __forceinline__ void seq_of(int row, int& s0, int& T) { if (row < MP) { s0 = row & ~2047; T = 2048; } else { s0 = MP + ((row - MP) & ~4095); T = 4096; } }
; __device__ __forceinline__ void a_decode(int un, int& s0, int& sh, int& r, int& n, int& u0, int& hd) {
;     const int t128 = un / 12; hd = un - t128 * 12; const int row0 = t128 * 128; int T; seq_of(row0, s0, T);
;     const int x = (row0 - s0) >> 7; sh = 2 * (hd >> 2); r = x & ((1 << sh) - 1); n = T >> sh; u0 = (x >> sh) * 128;
; }
; __device__ __forceinline__ void a_prefetch(const bf16* P, int un, int tid, int wave, int fr, int fq, v4u (&vpre)[4], bf16x8& Q0, bf16x8& Q1, bf16x8 (&K)[9][2]) {
;     int s0, sh, r, n, u0, hd; a_decode(un, s0, sh, r, n, u0, hd);
; #pragma unroll
;     for (int i = 0; i < 4; ++i) { const int e = tid + i * NTHREADS, kl = e >> 3, chunk = e & 7; int up = u0 - 64 + kl; up = up < 0 ? 0 : up; up = up > n - 1 ? n - 1 : up;
;         vpre[i] = *(const v4u*)(P + (size_t)(s0 + (up << sh) + r) * DIN + C_VA + hd * 64 + chunk * 8); }
;     { const int u = u0 + 16 * wave + fr; const bf16* qp = P + (size_t)(s0 + (u << sh) + r) * DIN + C_QA + hd * 64 + fq * 8; Q0 = *(const bf16x8*)qp; Q1 = *(const bf16x8*)(qp + 32); }
;     const int ub = u0 + 16 * wave - 64;
; #pragma unroll
;     for (int kt = 0; kt < 9; ++kt) { int up = ub + 16 * kt + fr; up = up < 0 ? 0 : up; up = up > n - 1 ? n - 1 : up;
;         const bf16* kp = P + (size_t)(s0 + (up << sh) + r) * DIN + C_KA + hd * 64 + fq * 8; K[kt][0] = *(const bf16x8*)kp; K[kt][1] = *(const bf16x8*)(kp + 32); }
; }
; __device__ __forceinline__ void mixA_mfma(const bf16* P, bf16* OG, float* LSE, LAS unsigned char* lds, int bid, int G, int tid) {
;     const int lane = tid & 63, wave = __builtin_amdgcn_readfirstlane(tid >> 6), fr = lane & 15, fq = lane >> 4;
;     LAS unsigned char* Vs = lds;
;     constexpr int NU = (M / 128) * 12;
;     constexpr float L2E = 1.4426950408889634f;
;     v4u vpre[4]; bf16x8 Qn0, Qn1, Kn[9][2];
;     if (bid < NU) a_prefetch(P, bid, tid, wave, fr, fq, vpre, Qn0, Qn1, Kn);
.LBB0_328:
.LBB0_329:
	s_cmp_lt_i32 s66, 3
	s_cselect_b64 s[20:21], -1, 0
	s_add_u32 s76, s64, 0x22500000
	s_addc_u32 s77, s65, 0
	s_add_u32 s4, s64, 0x29300000
	s_addc_u32 s5, s65, 0
	s_and_b64 s[0:1], s[20:21], s[0:1]
	v_writelane_b32 v238, s4, 29
	s_andn2_b64 vcc, exec, s[0:1]
	s_nop 0
	v_writelane_b32 v238, s5, 30
	s_cbranch_vccnz .LBB0_534
	v_and_b32_e32 v207, 15, v208
	v_readfirstlane_b32 s6, v208
	s_cmpk_gt_i32 s2, 0x8ff
	v_lshrrev_b32_e32 v137, 2, v207
	s_cbranch_scc1 .LBB0_337
	s_add_u32 s0, s64, 0x26d00000
	s_addc_u32 s1, s65, 0
	s_add_u32 s10, s64, 0x29100000
	s_mul_hi_i32 s3, s2, 0x2aaaaaab
	s_addc_u32 s11, s65, 0
	s_lshr_b32 s4, s3, 31
	s_ashr_i32 s3, s3, 1
	s_add_i32 s3, s3, s4
	s_mul_i32 s4, s3, -12
	s_add_i32 s4, s4, s2
	s_lshl_b32 s5, s3, 7
	s_cmpk_lt_i32 s2, 0x600
	s_movk_i32 s3, 0xf800
	s_cselect_b32 s7, s3, 0x7ffff000
	s_movk_i32 s12, 0x800
	s_cselect_b32 s8, s12, 0x1000
	s_and_b32 s7, s7, s5
	s_ashr_i32 s9, s4, 1
	s_sub_i32 s5, s5, s7
	s_and_b32 s14, s9, -2
	s_ashr_i32 s5, s5, 7
	s_lshl_b32 s9, -1, s14
	s_andn2_b32 s9, s5, s9
	s_ashr_i32 s5, s5, s14
	s_lshl_b32 s15, s5, 7
	v_lshrrev_b32_e32 v1, 3, v208
	v_add_u32_e32 v4, 0x200, v208
	v_add_u32_e32 v12, 0x600, v208
	s_sub_i32 s16, s15, 64
	v_lshrrev_b32_e32 v164, 3, v4
	v_or_b32_e32 v165, 0x80, v1
	v_lshrrev_b32_e32 v166, 3, v12
	s_lshr_b32 s8, s8, s14
	v_add_u32_e32 v2, s16, v1
	v_add_u32_e32 v4, s16, v164
	v_add_u32_e32 v10, s16, v165
	v_add_u32_e32 v12, s16, v166
	s_add_i32 s17, s8, -1
	v_max_i32_e32 v2, 0, v2
	v_max_i32_e32 v4, 0, v4
	v_max_i32_e32 v10, 0, v10
	v_max_i32_e32 v12, 0, v12
	v_min_i32_e32 v2, s17, v2
	v_min_i32_e32 v4, s17, v4
	v_min_i32_e32 v10, s17, v10
	v_min_i32_e32 v12, s17, v12
	s_add_i32 s18, s9, s7
	v_lshlrev_b32_e32 v2, s14, v2
	v_lshlrev_b32_e32 v4, s14, v4
	v_lshlrev_b32_e32 v10, s14, v10
	v_lshlrev_b32_e32 v12, s14, v12
	v_add_u32_e32 v2, s18, v2
	s_movk_i32 s13, 0x2c00
	v_mov_b64_e32 v[90:91], s[74:75]
	v_add_u32_e32 v4, s18, v4
	v_add_u32_e32 v10, s18, v10
	v_add_u32_e32 v12, s18, v12
	s_lshr_b32 s6, s6, 2
	v_mad_i64_i32 v[2:3], s[8:9], v2, s13, v[90:91]
	v_mad_i64_i32 v[4:5], s[8:9], v4, s13, v[90:91]
	v_mad_i64_i32 v[10:11], s[8:9], v10, s13, v[90:91]
	v_mad_i64_i32 v[12:13], s[8:9], v12, s13, v[90:91]
	s_and_b32 s22, s6, 0x3ffffff0
	s_add_i32 s8, s22, s15
	v_or_b32_e32 v18, s8, v207
	v_lshlrev_b32_e32 v18, s14, v18
	v_add_u32_e32 v18, s18, v18
	v_mad_i64_i32 v[18:19], s[6:7], v18, s13, v[90:91]
	s_sub_i32 s6, s8, 64
	s_nop 0
	v_or_b32_e32 v92, s6, v207
	v_max_i32_e32 v26, 0, v92
	v_add_u32_e32 v34, 16, v92
	v_add_u32_e32 v42, 32, v92
	v_add_u32_e32 v50, 48, v92
	v_add_u32_e32 v58, 64, v92
	v_add_u32_e32 v66, 0x50, v92
	v_add_u32_e32 v74, 0x60, v92
	v_add_u32_e32 v82, 0x70, v92
	v_add_u32_e32 v92, 0x80, v92
	v_max_i32_e32 v34, 0, v34
	v_max_i32_e32 v42, 0, v42
	v_max_i32_e32 v50, 0, v50
	v_max_i32_e32 v58, 0, v58
	v_max_i32_e32 v66, 0, v66
	v_max_i32_e32 v74, 0, v74
	v_max_i32_e32 v82, 0, v82
	v_max_i32_e32 v92, 0, v92
	s_lshl_b32 s4, s4, 6
	v_min_i32_e32 v26, s17, v26
	v_min_i32_e32 v34, s17, v34
	v_min_i32_e32 v42, s17, v42
	v_min_i32_e32 v50, s17, v50
	v_min_i32_e32 v58, s17, v58
	v_min_i32_e32 v66, s17, v66
	v_min_i32_e32 v74, s17, v74
	v_min_i32_e32 v82, s17, v82
	v_min_i32_e32 v92, s17, v92
	s_ashr_i32 s5, s4, 31
	v_lshlrev_b32_e32 v101, 3, v208
	v_lshlrev_b32_e32 v26, s14, v26
	v_lshlrev_b32_e32 v34, s14, v34
	v_lshlrev_b32_e32 v42, s14, v42
	v_lshlrev_b32_e32 v50, s14, v50
	v_lshlrev_b32_e32 v58, s14, v58
	v_lshlrev_b32_e32 v66, s14, v66
	v_lshlrev_b32_e32 v74, s14, v74
	v_lshlrev_b32_e32 v82, s14, v82
	v_lshlrev_b32_e32 v92, s14, v92
	v_and_b32_e32 v98, 56, v101
	s_lshl_b64 s[4:5], s[4:5], 1
	v_add_u32_e32 v26, s18, v26
	v_add_u32_e32 v34, s18, v34
	v_add_u32_e32 v42, s18, v42
	v_add_u32_e32 v50, s18, v50
	v_add_u32_e32 v58, s18, v58
	v_add_u32_e32 v66, s18, v66
	v_add_u32_e32 v74, s18, v74
	v_add_u32_e32 v82, s18, v82
	v_add_u32_e32 v92, s18, v92
	v_bfe_u32 v99, v208, 4, 2
	v_mov_b32_e32 v135, 0
	v_lshl_add_u64 v[2:3], v[2:3], 0, s[4:5]
	v_lshlrev_b32_e32 v134, 1, v98
	v_lshl_add_u64 v[4:5], v[4:5], 0, s[4:5]
	v_lshl_add_u64 v[10:11], v[10:11], 0, s[4:5]
	v_lshl_add_u64 v[12:13], v[12:13], 0, s[4:5]
	v_mad_i64_i32 v[26:27], s[6:7], v26, s13, v[90:91]
	v_mad_i64_i32 v[34:35], s[6:7], v34, s13, v[90:91]
	v_mad_i64_i32 v[42:43], s[6:7], v42, s13, v[90:91]
	v_mad_i64_i32 v[50:51], s[6:7], v50, s13, v[90:91]
	v_mad_i64_i32 v[58:59], s[6:7], v58, s13, v[90:91]
	v_mad_i64_i32 v[66:67], s[6:7], v66, s13, v[90:91]
; __device__ __forceinline__ void a_prefetch(const bf16* P, int un, int tid, int wave, int fr, int fq, v4u (&vpre)[4], bf16x8& Q0, bf16x8& Q1, bf16x8 (&K)[9][2]) {
;     int s0, sh, r, n, u0, hd; a_decode(un, s0, sh, r, n, u0, hd);
; #pragma unroll
;     for (int i = 0; i < 4; ++i) { const int e = tid + i * NTHREADS, kl = e >> 3, chunk = e & 7; int up = u0 - 64 + kl; up = up < 0 ? 0 : up; up = up > n - 1 ? n - 1 : up;
;         vpre[i] = *(const v4u*)(P + (size_t)(s0 + (up << sh) + r) * DIN + C_VA + hd * 64 + chunk * 8); }
;     { const int u = u0 + 16 * wave + fr; const bf16* qp = P + (size_t)(s0 + (u << sh) + r) * DIN + C_QA + hd * 64 + fq * 8; Q0 = *(const bf16x8*)qp; Q1 = *(const bf16x8*)(qp + 32); }
;     const int ub = u0 + 16 * wave - 64;
; #pragma unroll
;     for (int kt = 0; kt < 9; ++kt) { int up = ub + 16 * kt + fr; up = up < 0 ? 0 : up; up = up > n - 1 ? n - 1 : up;
;         const bf16* kp = P + (size_t)(s0 + (up << sh) + r) * DIN + C_KA + hd * 64 + fq * 8; K[kt][0] = *(const bf16x8*)kp; K[kt][1] = *(const bf16x8*)(kp + 32); }
; }
; __device__ __forceinline__ void mixA_mfma(const bf16* P, bf16* OG, float* LSE, LAS unsigned char* lds, int bid, int G, int tid) {
;     ...
;         const int u = u0 + 16 * wave + fr;
;         const size_t qrow = (size_t)(s0 + (u << sh) + r);
;         f32x4 S[10];
;         const int ub = u0 + 16 * wave - 64;
; #pragma unroll
;         for (int kt = 0; kt < 9; ++kt) { f32x4 z = {0.f, 0.f, 0.f, 0.f};
;             z = __builtin_amdgcn_mfma_f32_16x16x32_bf16(Kn[kt][0], Qn0, z, 0, 0, 0);
;             S[kt] = __builtin_amdgcn_mfma_f32_16x16x32_bf16(Kn[kt][1], Qn1, z, 0, 0, 0); }
;         asm volatile("" ::: "memory");
;         if (un + G < NU) a_prefetch(P, un + G, tid, wave, fr, fq, vpre, Qn0, Qn1, Kn);
;         float mx = -1e30f;
; #pragma unroll
;         for (int kt = 0; kt < 9; ++kt)
; #pragma unroll
;             for (int t = 0; t < 4; ++t) {
;                 const int up = ub + 16 * kt + 4 * fq + t; const int rel = up > u ? up - u : u - up; const bool ok = rel <= 64 && up >= 0 && up < n;
;                 const float s = ok ? S[kt][t] * (0.125f * L2E) - slope * (float)rel : -1e30f;
;                 S[kt][t] = s; mx = fmaxf(mx, s);
;             }
;         mx = fmaxf(mx, __shfl_xor(mx, 16)); mx = fmaxf(mx, __shfl_xor(mx, 32));
;         float den = 0.f;
; #pragma unroll
;         for (int kt = 0; kt < 9; ++kt)
	v_mad_i64_i32 v[74:75], s[6:7], v74, s13, v[90:91]
	v_mad_i64_i32 v[82:83], s[6:7], v82, s13, v[90:91]
	v_mad_i64_i32 v[90:91], s[6:7], v92, s13, v[90:91]
	v_lshl_add_u64 v[2:3], v[2:3], 0, v[134:135]
	v_lshl_add_u64 v[6:7], v[4:5], 0, v[134:135]
	v_lshl_add_u64 v[10:11], v[10:11], 0, v[134:135]
	v_lshl_add_u64 v[14:15], v[12:13], 0, v[134:135]
	v_lshl_add_u64 v[18:19], v[18:19], 0, s[4:5]
	v_lshlrev_b32_e32 v134, 4, v99
	v_lshl_add_u64 v[26:27], v[26:27], 0, s[4:5]
	v_lshl_add_u64 v[34:35], v[34:35], 0, s[4:5]
	v_lshl_add_u64 v[42:43], v[42:43], 0, s[4:5]
	v_lshl_add_u64 v[50:51], v[50:51], 0, s[4:5]
	v_lshl_add_u64 v[58:59], v[58:59], 0, s[4:5]
	v_lshl_add_u64 v[66:67], v[66:67], 0, s[4:5]
	v_lshl_add_u64 v[74:75], v[74:75], 0, s[4:5]
	v_lshl_add_u64 v[82:83], v[82:83], 0, s[4:5]
	v_lshl_add_u64 v[90:91], v[90:91], 0, s[4:5]
	v_lshl_add_u64 v[22:23], v[18:19], 0, v[134:135]
	v_lshl_add_u64 v[30:31], v[26:27], 0, v[134:135]
	v_lshl_add_u64 v[38:39], v[34:35], 0, v[134:135]
	v_lshl_add_u64 v[46:47], v[42:43], 0, v[134:135]
	v_lshl_add_u64 v[54:55], v[50:51], 0, v[134:135]
	v_lshl_add_u64 v[62:63], v[58:59], 0, v[134:135]
	v_lshl_add_u64 v[70:71], v[66:67], 0, v[134:135]
	v_lshl_add_u64 v[78:79], v[74:75], 0, v[134:135]
	v_lshl_add_u64 v[86:87], v[82:83], 0, v[134:135]
	v_lshl_add_u64 v[94:95], v[90:91], 0, v[134:135]
	v_and_b32_e32 v239, 15, v208
	v_lshrrev_b32_e32 v255, 6, v208
	v_lshl_or_b32 v239, v255, 4, v239
	v_mul_u32_u24_e32 v239, 0xa0, v239
	v_bfe_u32 v255, v208, 4, 2
	v_lshl_add_u32 v239, v255, 4, v239
	global_load_dwordx4 v[240:243], v[2:3], off offset:1536
	global_load_dwordx4 v[244:247], v[6:7], off offset:1536
	global_load_dwordx4 v[248:251], v[10:11], off offset:1536
	global_load_dwordx4 v[252:255], v[14:15], off offset:1536
	global_load_dwordx4 v[2:5], v[2:3], off offset:3072
	s_nop 0
	global_load_dwordx4 v[6:9], v[6:7], off offset:3072
	s_nop 0
	global_load_dwordx4 v[10:13], v[10:11], off offset:3072
	s_nop 0
	global_load_dwordx4 v[14:17], v[14:15], off offset:3072
	s_nop 0
	global_load_dwordx4 v[18:21], v[22:23], off
	s_nop 0
	global_load_dwordx4 v[22:25], v[22:23], off offset:64
	v_lshlrev_b32_e32 v136, 2, v99
	v_sub_u32_e32 v106, v136, v207
	v_sub_u32_e32 v107, 0, v106
	v_max_i32_e32 v106, v106, v107
	v_or_b32_e32 v168, 0xffffffc0, v136
	v_cvt_f32_u32_e32 v139, v106
	v_or_b32_e32 v169, 0xffffffd0, v136
	v_sub_u32_e32 v106, v207, v168
	s_movk_i32 s26, 0x41
	v_or_b32_e32 v170, 0xffffffe0, v136
	v_cmp_gt_u32_e64 s[6:7], s26, v106
	v_cvt_f32_ubyte0_e32 v141, v106
	v_sub_u32_e32 v106, v207, v169
	v_or_b32_e32 v171, -16, v136
	v_cvt_f32_ubyte0_e32 v143, v106
	v_sub_u32_e32 v106, v207, v170
	v_or_b32_e32 v172, 16, v136
	v_cvt_f32_ubyte0_e32 v145, v106
	v_sub_u32_e32 v106, v207, v171
	v_or_b32_e32 v173, 32, v136
	v_cvt_f32_ubyte0_e32 v147, v106
	v_sub_u32_e32 v106, v172, v207
	v_lshlrev_b32_e32 v102, 4, v208
	v_or3_b32 v103, v137, v136, s22
	s_movk_i32 s4, 0xa0
	v_or_b32_e32 v174, 48, v136
	v_cvt_f32_ubyte0_e32 v149, v106
	v_sub_u32_e32 v106, v173, v207
	v_and_b32_e32 v102, 0x70, v102
	v_mul_lo_u32 v103, v103, s4
	v_or_b32_e32 v175, 64, v136
	v_cvt_f32_ubyte0_e32 v151, v106
	v_sub_u32_e32 v106, v174, v207
	v_lshlrev_b32_e32 v100, 3, v99
	v_add_u32_e32 v102, 0, v102
	v_add_u32_e32 v103, 0, v103
	v_and_b32_e32 v101, 24, v101
	v_cmp_eq_u32_e64 s[4:5], 0, v99
	v_mul_u32_u24_e32 v99, 0xa0, v1
	v_mul_u32_u24_e32 v104, 0xa0, v164
	v_mul_u32_u24_e32 v105, 0xa0, v166
	v_cvt_f32_ubyte0_e32 v153, v106
	v_sub_u32_e32 v106, v175, v207
	v_lshlrev_b32_e32 v158, 1, v98
	v_mbcnt_lo_u32_b32 v98, -1, 0
	s_movk_i32 s23, 0x600
	v_or_b32_e32 v167, 0xffffffc0, v207
	v_cmp_gt_u32_e64 s[8:9], s26, v106
	v_cvt_f32_ubyte0_e32 v155, v106
	v_mov_b32_e32 v156, 0x3e38aa3b
	v_mov_b32_e32 v154, 0x3e38aa3b
	v_mov_b32_e32 v152, 0x3e38aa3b
	v_mov_b32_e32 v150, 0x3e38aa3b
	v_mov_b32_e32 v148, 0x3e38aa3b
	v_mov_b32_e32 v138, 0x3e38aa3b
	v_mov_b32_e32 v146, 0x3e38aa3b
	v_mov_b32_e32 v144, 0x3e38aa3b
	v_mov_b32_e32 v142, 0x3e38aa3b
	v_mov_b32_e32 v140, 0x3e38aa3b
	s_lshl_b32 s27, s68, 6
	s_lshl_b32 s29, s2, 6
	s_mov_b32 s31, 0x41400000
	s_mov_b32 s33, 0xc2fc0000
	v_add_u32_e32 v176, v102, v99
	v_add_u32_e32 v177, v102, v104
	v_add_u32_e32 v178, v102, v105
	v_lshlrev_b32_e32 v160, 1, v100
	s_mov_b32 s34, 0xf149f2ca
	v_mbcnt_hi_u32_b32 v179, -1, v98
	v_add_u32_e32 v180, v103, v101
	v_mov_b32_e32 v181, 0x42800000
	v_mov_b32_e32 v182, 0xf149f2ca
	s_mov_b32 s78, s2
	s_waitcnt vmcnt(0)
	s_branch .LBB0_333

; #define LAS __attribute__((address_space(3)))
; __device__ __forceinline__ void mixA_mfma(const bf16* P, bf16* OG, float* LSE, LAS unsigned char* lds, int bid, int G, int tid) {
;     ...
;     for (int un = bid; un < NU; un += G) {
;         int s0, sh, r, n, u0, hd; a_decode(un, s0, sh, r, n, u0, hd);
;         const float slope = exp2f(-8.0f * (float)(hd + 1) / 12.0f) * (float)(1 << sh) * L2E;
;         __syncthreads();
; #pragma unroll
;         for (int i = 0; i < 4; ++i) { const int e = tid + i * NTHREADS; *(LAS v4u*)(Vs + (e >> 3) * VROW + (e & 7) * 16) = vpre[i]; }
;         __syncthreads();
;         const int u = u0 + 16 * wave + fr;
;         const size_t qrow = (size_t)(s0 + (u << sh) + r);
;         f32x4 S[10];
;         const int ub = u0 + 16 * wave - 64;
; #pragma unroll
;         for (int kt = 0; kt < 9; ++kt) { f32x4 z = {0.f, 0.f, 0.f, 0.f};
;             z = __builtin_amdgcn_mfma_f32_16x16x32_bf16(Kn[kt][0], Qn0, z, 0, 0, 0);
;             S[kt] = __builtin_amdgcn_mfma_f32_16x16x32_bf16(Kn[kt][1], Qn1, z, 0, 0, 0); }
.LBB0_333:
	s_mul_hi_i32 s14, s78, 0x2aaaaaab
	s_lshr_b32 s15, s14, 31
	s_ashr_i32 s14, s14, 1
	s_waitcnt vmcnt(5)
	s_barrier
	ds_write_b128 v176, v[2:5]
	ds_write_b128 v177, v[6:9]
	ds_write_b128 v176, v[10:13] offset:20480
	ds_write_b128 v178, v[14:17]
	ds_write_b128 v176, v[240:243] offset:40960
	ds_write_b128 v177, v[244:247] offset:40960
	ds_write_b128 v176, v[248:251] offset:61440
	ds_write_b128 v178, v[252:255] offset:40960
	s_waitcnt lgkmcnt(0)
	s_barrier
	ds_read_b128 v[26:29], v239 offset:40960
	ds_read_b128 v[30:33], v239 offset:41024
	ds_read_b128 v[34:37], v239 offset:43520
	ds_read_b128 v[38:41], v239 offset:43584
	ds_read_b128 v[42:45], v239 offset:46080
	ds_read_b128 v[46:49], v239 offset:46144
	ds_read_b128 v[50:53], v239 offset:48640
	ds_read_b128 v[54:57], v239 offset:48704
	ds_read_b128 v[58:61], v239 offset:51200
	ds_read_b128 v[62:65], v239 offset:51264
	ds_read_b128 v[66:69], v239 offset:53760
	ds_read_b128 v[70:73], v239 offset:53824
	ds_read_b128 v[74:77], v239 offset:56320
	ds_read_b128 v[78:81], v239 offset:56384
	s_waitcnt lgkmcnt(13)
	v_mfma_f32_16x16x32_bf16 v[98:101], v[26:29], v[18:21], 0
	s_add_i32 s15, s14, s15
	s_mul_i32 s14, s15, -12
	s_add_i32 s14, s78, s14
	s_add_i32 s16, s14, 1
	s_waitcnt lgkmcnt(12)
	v_mfma_f32_16x16x32_bf16 v[130:133], v[30:33], v[22:25], v[98:101]
	v_cvt_f32_i32_e32 v102, s16
	s_waitcnt lgkmcnt(11)
	v_mfma_f32_16x16x32_bf16 v[98:101], v[34:37], v[18:21], 0
	v_mul_f32_e32 v102, 0xc1000000, v102
	v_div_scale_f32 v103, s[16:17], s31, s31, v102
	s_waitcnt lgkmcnt(10)
	v_mfma_f32_16x16x32_bf16 v[126:129], v[38:41], v[22:25], v[98:101]
	v_rcp_f32_e32 v104, v103
	ds_read_b128 v[82:85], v239 offset:58880
	ds_read_b128 v[86:89], v239 offset:58944
	ds_read_b128 v[90:93], v239 offset:61440
	ds_read_b128 v[94:97], v239 offset:61504
	s_waitcnt lgkmcnt(13)
	v_mfma_f32_16x16x32_bf16 v[98:101], v[42:45], v[18:21], 0
	v_fma_f32 v105, -v103, v104, 1.0
	v_fmac_f32_e32 v104, v105, v104
	v_div_scale_f32 v105, vcc, v102, s31, v102
	s_waitcnt lgkmcnt(12)
	v_mfma_f32_16x16x32_bf16 v[122:125], v[46:49], v[22:25], v[98:101]
	v_mul_f32_e32 v106, v105, v104
	v_fma_f32 v107, -v103, v106, v105
	v_fmac_f32_e32 v106, v107, v104
	s_waitcnt lgkmcnt(11)
	v_mfma_f32_16x16x32_bf16 v[98:101], v[50:53], v[18:21], 0
	v_fma_f32 v103, -v103, v106, v105
	s_waitcnt lgkmcnt(10)
	v_mfma_f32_16x16x32_bf16 v[118:121], v[54:57], v[22:25], v[98:101]
	s_waitcnt lgkmcnt(9)
	v_mfma_f32_16x16x32_bf16 v[98:101], v[58:61], v[18:21], 0
	s_waitcnt lgkmcnt(8)
	v_mfma_f32_16x16x32_bf16 v[114:117], v[62:65], v[22:25], v[98:101]
	s_nop 6
	v_div_fmas_f32 v98, v103, v104, v106
	v_div_fixup_f32 v102, v98, s31, v102
	s_waitcnt lgkmcnt(7)
	v_mfma_f32_16x16x32_bf16 v[98:101], v[66:69], v[18:21], 0
	v_cmp_gt_f32_e32 vcc, s33, v102
	s_and_b64 s[16:17], vcc, exec
	s_cselect_b32 s16, 0xffffffc0, 0
	s_waitcnt lgkmcnt(6)
	v_mfma_f32_16x16x32_bf16 v[110:113], v[70:73], v[22:25], v[98:101]
	v_cndmask_b32_e32 v103, 0, v181, vcc
	v_add_f32_e32 v102, v102, v103
	v_exp_f32_e32 v102, v102
	s_waitcnt lgkmcnt(5)
	v_mfma_f32_16x16x32_bf16 v[98:101], v[74:77], v[18:21], 0
	s_add_i32 s35, s78, s68
	s_cmpk_gt_i32 s35, 0x8ff
	v_ldexp_f32 v134, v102, s16
	s_waitcnt lgkmcnt(4)
	v_mfma_f32_16x16x32_bf16 v[106:109], v[78:81], v[22:25], v[98:101]
	s_cselect_b64 s[16:17], -1, 0
	s_and_b64 vcc, exec, s[16:17]
	s_waitcnt lgkmcnt(3)
	v_mfma_f32_16x16x32_bf16 v[98:101], v[82:85], v[18:21], 0
	s_waitcnt lgkmcnt(2)
	v_mfma_f32_16x16x32_bf16 v[102:105], v[86:89], v[22:25], v[98:101]
	s_waitcnt lgkmcnt(1)
	v_mfma_f32_16x16x32_bf16 v[98:101], v[90:93], v[18:21], 0
	s_waitcnt lgkmcnt(0)
	v_mfma_f32_16x16x32_bf16 v[98:101], v[94:97], v[22:25], v[98:101]
	s_cbranch_vccnz .LBB0_335
; __device__ __forceinline__ void seq_of(int row, int& s0, int& T) { if (row < MP) { s0 = row & ~2047; T = 2048; } else { s0 = MP + ((row - MP) & ~4095); T = 4096; } }
; __device__ __forceinline__ void a_decode(int un, int& s0, int& sh, int& r, int& n, int& u0, int& hd) {
;     const int t128 = un / 12; hd = un - t128 * 12; const int row0 = t128 * 128; int T; seq_of(row0, s0, T);
;     const int x = (row0 - s0) >> 7; sh = 2 * (hd >> 2); r = x & ((1 << sh) - 1); n = T >> sh; u0 = (x >> sh) * 128;
; }
; __device__ __forceinline__ void a_prefetch(const bf16* P, int un, int tid, int wave, int fr, int fq, v4u (&vpre)[4], bf16x8& Q0, bf16x8& Q1, bf16x8 (&K)[9][2]) {
;     int s0, sh, r, n, u0, hd; a_decode(un, s0, sh, r, n, u0, hd);
; #pragma unroll
;     for (int i = 0; i < 4; ++i) { const int e = tid + i * NTHREADS, kl = e >> 3, chunk = e & 7; int up = u0 - 64 + kl; up = up < 0 ? 0 : up; up = up > n - 1 ? n - 1 : up;
;         vpre[i] = *(const v4u*)(P + (size_t)(s0 + (up << sh) + r) * DIN + C_VA + hd * 64 + chunk * 8); }
;     { const int u = u0 + 16 * wave + fr; const bf16* qp = P + (size_t)(s0 + (u << sh) + r) * DIN + C_QA + hd * 64 + fq * 8; Q0 = *(const bf16x8*)qp; Q1 = *(const bf16x8*)(qp + 32); }
;     const int ub = u0 + 16 * wave - 64;
; #pragma unroll
;     for (int kt = 0; kt < 9; ++kt) { int up = ub + 16 * kt + fr; up = up < 0 ? 0 : up; up = up > n - 1 ? n - 1 : up;
;         const bf16* kp = P + (size_t)(s0 + (up << sh) + r) * DIN + C_KA + hd * 64 + fq * 8; K[kt][0] = *(const bf16x8*)kp; K[kt][1] = *(const bf16x8*)(kp + 32); }
; }
; __device__ __forceinline__ void mixA_mfma(const bf16* P, bf16* OG, float* LSE, LAS unsigned char* lds, int bid, int G, int tid) {
;     ...
;         if (un + G < NU) a_prefetch(P, un + G, tid, wave, fr, fq, vpre, Qn0, Qn1, Kn);
	s_mul_hi_i32 s18, s35, 0x2aaaaaab
	s_lshr_b32 s19, s18, 31
	s_ashr_i32 s18, s18, 1
	s_add_i32 s18, s18, s19
	s_mul_i32 s19, s18, -12
	s_add_i32 s19, s35, s19
	s_lshl_b32 s24, s18, 7
	s_cmpk_lt_i32 s35, 0x600
	s_cselect_b32 s25, s3, 0x7ffff000
	s_cselect_b32 s36, s12, 0x1000
	s_and_b32 s25, s25, s24
	s_ashr_i32 s19, s19, 1
	s_sub_i32 s24, s24, s25
	s_and_b32 s37, s19, -2
	s_ashr_i32 s24, s24, 7
	s_lshl_b32 s19, -1, s37
	s_andn2_b32 s19, s24, s19
	s_ashr_i32 s24, s24, s37
	s_lshl_b32 s38, s24, 7
	s_sub_i32 s39, s38, 64
	s_add_i32 s38, s38, s22
	v_add_u32_e32 v92, s38, v167
	s_lshr_b32 s36, s36, s37
	v_add_u32_e32 v2, s39, v1
	v_add_u32_e32 v4, s39, v164
	v_add_u32_e32 v10, s39, v165
	v_add_u32_e32 v12, s39, v166
	v_max_i32_e32 v26, 0, v92
	v_add_u32_e32 v34, 16, v92
	v_add_u32_e32 v42, 32, v92
	v_add_u32_e32 v50, 48, v92
	v_add_u32_e32 v58, 64, v92
	v_add_u32_e32 v66, 0x50, v92
	v_add_u32_e32 v74, 0x60, v92
	v_add_u32_e32 v82, 0x70, v92
	v_add_u32_e32 v92, 0x80, v92
	s_add_i32 s36, s36, -1
	v_max_i32_e32 v2, 0, v2
	v_max_i32_e32 v4, 0, v4
	v_max_i32_e32 v10, 0, v10
	v_max_i32_e32 v12, 0, v12
	v_max_i32_e32 v34, 0, v34
	v_max_i32_e32 v42, 0, v42
	v_max_i32_e32 v50, 0, v50
	v_max_i32_e32 v58, 0, v58
	v_max_i32_e32 v66, 0, v66
	v_max_i32_e32 v74, 0, v74
	v_max_i32_e32 v82, 0, v82
	v_max_i32_e32 v92, 0, v92
	s_add_i32 s40, s19, s25
	s_mulk_i32 s18, 0xfd00
	s_add_i32 s19, s27, s29
	v_min_i32_e32 v2, s36, v2
	v_min_i32_e32 v4, s36, v4
	v_min_i32_e32 v10, s36, v10
	v_min_i32_e32 v12, s36, v12
	v_or_b32_e32 v18, s38, v207
	v_min_i32_e32 v26, s36, v26
	v_min_i32_e32 v34, s36, v34
	v_min_i32_e32 v42, s36, v42
	v_min_i32_e32 v50, s36, v50
	v_min_i32_e32 v58, s36, v58
	v_min_i32_e32 v66, s36, v66
	v_min_i32_e32 v74, s36, v74
	v_min_i32_e32 v82, s36, v82
	v_min_i32_e32 v92, s36, v92
	s_add_i32 s18, s19, s18
	v_lshlrev_b32_e32 v2, s37, v2
	v_lshlrev_b32_e32 v4, s37, v4
	v_lshlrev_b32_e32 v10, s37, v10
	v_lshlrev_b32_e32 v12, s37, v12
	v_lshlrev_b32_e32 v18, s37, v18
	v_lshlrev_b32_e32 v26, s37, v26
	v_lshlrev_b32_e32 v34, s37, v34
	v_lshlrev_b32_e32 v42, s37, v42
	v_lshlrev_b32_e32 v50, s37, v50
	v_lshlrev_b32_e32 v58, s37, v58
	v_lshlrev_b32_e32 v66, s37, v66
	v_lshlrev_b32_e32 v74, s37, v74
	v_lshlrev_b32_e32 v82, s37, v82
	v_lshlrev_b32_e32 v92, s37, v92
	s_ashr_i32 s19, s18, 31
	v_add_u32_e32 v2, s40, v2
	v_mov_b64_e32 v[90:91], s[74:75]
	v_add_u32_e32 v4, s40, v4
	v_add_u32_e32 v10, s40, v10
	v_add_u32_e32 v12, s40, v12
	v_add_u32_e32 v18, s40, v18
	v_add_u32_e32 v26, s40, v26
	v_add_u32_e32 v34, s40, v34
	v_add_u32_e32 v42, s40, v42
	v_add_u32_e32 v50, s40, v50
	v_add_u32_e32 v58, s40, v58
	v_add_u32_e32 v66, s40, v66
	v_add_u32_e32 v74, s40, v74
	v_add_u32_e32 v82, s40, v82
	v_add_u32_e32 v92, s40, v92
	v_mad_i64_i32 v[2:3], s[24:25], v2, s13, v[90:91]
	s_lshl_b64 s[18:19], s[18:19], 1
	v_mad_i64_i32 v[4:5], s[24:25], v4, s13, v[90:91]
	v_mad_i64_i32 v[10:11], s[24:25], v10, s13, v[90:91]
	v_mad_i64_i32 v[12:13], s[24:25], v12, s13, v[90:91]
	v_mad_i64_i32 v[18:19], s[24:25], v18, s13, v[90:91]
	v_mad_i64_i32 v[26:27], s[24:25], v26, s13, v[90:91]
	v_mad_i64_i32 v[34:35], s[24:25], v34, s13, v[90:91]
	v_mad_i64_i32 v[42:43], s[24:25], v42, s13, v[90:91]
	v_mad_i64_i32 v[50:51], s[24:25], v50, s13, v[90:91]
	v_mad_i64_i32 v[58:59], s[24:25], v58, s13, v[90:91]
	v_mad_i64_i32 v[66:67], s[24:25], v66, s13, v[90:91]
	v_mad_i64_i32 v[74:75], s[24:25], v74, s13, v[90:91]
	v_mad_i64_i32 v[82:83], s[24:25], v82, s13, v[90:91]
	v_mad_i64_i32 v[90:91], s[24:25], v92, s13, v[90:91]
	v_lshl_add_u64 v[2:3], v[2:3], 0, s[18:19]
	v_mov_b32_e32 v159, v135
	v_lshl_add_u64 v[4:5], v[4:5], 0, s[18:19]
	v_lshl_add_u64 v[10:11], v[10:11], 0, s[18:19]
	v_lshl_add_u64 v[12:13], v[12:13], 0, s[18:19]
	v_lshl_add_u64 v[18:19], v[18:19], 0, s[18:19]
	v_mov_b32_e32 v161, v135
	v_lshl_add_u64 v[26:27], v[26:27], 0, s[18:19]
	v_lshl_add_u64 v[34:35], v[34:35], 0, s[18:19]
	v_lshl_add_u64 v[42:43], v[42:43], 0, s[18:19]
	v_lshl_add_u64 v[50:51], v[50:51], 0, s[18:19]
	v_lshl_add_u64 v[58:59], v[58:59], 0, s[18:19]
	v_lshl_add_u64 v[66:67], v[66:67], 0, s[18:19]
	v_lshl_add_u64 v[74:75], v[74:75], 0, s[18:19]
	v_lshl_add_u64 v[82:83], v[82:83], 0, s[18:19]
	v_lshl_add_u64 v[90:91], v[90:91], 0, s[18:19]
	v_lshl_add_u64 v[2:3], v[2:3], 0, v[158:159]
	v_lshl_add_u64 v[6:7], v[4:5], 0, v[158:159]
	v_lshl_add_u64 v[10:11], v[10:11], 0, v[158:159]
	v_lshl_add_u64 v[14:15], v[12:13], 0, v[158:159]
	v_lshl_add_u64 v[22:23], v[18:19], 0, v[160:161]
	v_lshl_add_u64 v[30:31], v[26:27], 0, v[160:161]
	v_lshl_add_u64 v[38:39], v[34:35], 0, v[160:161]
	v_lshl_add_u64 v[46:47], v[42:43], 0, v[160:161]
	v_lshl_add_u64 v[54:55], v[50:51], 0, v[160:161]
	v_lshl_add_u64 v[62:63], v[58:59], 0, v[160:161]
	v_lshl_add_u64 v[70:71], v[66:67], 0, v[160:161]
	v_lshl_add_u64 v[78:79], v[74:75], 0, v[160:161]
	v_lshl_add_u64 v[86:87], v[82:83], 0, v[160:161]
	v_lshl_add_u64 v[94:95], v[90:91], 0, v[160:161]
	global_load_dwordx4 v[240:243], v[2:3], off offset:1536
	global_load_dwordx4 v[244:247], v[6:7], off offset:1536
	global_load_dwordx4 v[248:251], v[10:11], off offset:1536
	global_load_dwordx4 v[252:255], v[14:15], off offset:1536
	global_load_dwordx4 v[2:5], v[2:3], off offset:3072
	s_nop 0
	global_load_dwordx4 v[6:9], v[6:7], off offset:3072
	s_nop 0
	global_load_dwordx4 v[10:13], v[10:11], off offset:3072
	s_nop 0
	global_load_dwordx4 v[14:17], v[14:15], off offset:3072
	s_nop 0
	global_load_dwordx4 v[18:21], v[22:23], off
	s_nop 0
	global_load_dwordx4 v[22:25], v[22:23], off offset:64

; #define LAS __attribute__((address_space(3)))
; __device__ __forceinline__ void seq_of(int row, int& s0, int& T) { if (row < MP) { s0 = row & ~2047; T = 2048; } else { s0 = MP + ((row - MP) & ~4095); T = 4096; } }
; __device__ __forceinline__ void a_decode(int un, int& s0, int& sh, int& r, int& n, int& u0, int& hd) {
;     const int t128 = un / 12; hd = un - t128 * 12; const int row0 = t128 * 128; int T; seq_of(row0, s0, T);
;     const int x = (row0 - s0) >> 7; sh = 2 * (hd >> 2); r = x & ((1 << sh) - 1); n = T >> sh; u0 = (x >> sh) * 128;
; __device__ __forceinline__ void mixA_mfma(const bf16* P, bf16* OG, float* LSE, LAS unsigned char* lds, int bid, int G, int tid) {
;     const int lane = tid & 63, wave = __builtin_amdgcn_readfirstlane(tid >> 6), fr = lane & 15, fq = lane >> 4;
;     LAS unsigned char* Vs = lds;
;     constexpr int NU = (M / 128) * 12;
;     constexpr float L2E = 1.4426950408889634f;
;     v4u vpre[4]; bf16x8 Qn0, Qn1, Kn[9][2];
;     if (bid < NU) a_prefetch(P, bid, tid, wave, fr, fq, vpre, Qn0, Qn1, Kn);
.LBB0_1354:
	s_cmp_lt_i32 s66, 10
	s_cselect_b64 s[48:49], -1, 0
	s_add_u32 s46, s52, 0x2000
	s_addc_u32 s47, s53, 0
	s_add_u32 s3, s56, 0x40000
	s_addc_u32 s34, s57, 0
	s_add_u32 s44, s58, 0x1000
	s_addc_u32 s45, s59, 0
	v_readlane_b32 s4, v238, 13
	v_readlane_b32 s5, v238, 14
	s_add_u32 s58, s4, 0x40000
	v_readlane_b32 s6, v238, 15
	s_addc_u32 s59, s5, 0
	v_readlane_b32 s7, v238, 16
	s_add_u32 s36, s6, 0x1000
	v_readlane_b32 s8, v238, 17
	s_addc_u32 s37, s7, 0
	v_readlane_b32 s9, v238, 18
	s_add_u32 s38, s8, 0x1000
	s_addc_u32 s39, s9, 0
	s_and_b64 s[0:1], s[48:49], s[0:1]
	s_andn2_b64 vcc, exec, s[0:1]
	v_readlane_b32 s10, v238, 19
	v_readlane_b32 s11, v238, 20
	v_readlane_b32 s12, v238, 21
	v_readlane_b32 s13, v238, 22
	v_readlane_b32 s14, v238, 23
	v_readlane_b32 s15, v238, 24
	v_readlane_b32 s16, v238, 25
	v_readlane_b32 s17, v238, 26
	v_readlane_b32 s18, v238, 27
	v_readlane_b32 s19, v238, 28
	s_cbranch_vccnz .LBB0_1559
	v_and_b32_e32 v213, 15, v208
	v_readfirstlane_b32 s6, v208
	s_cmpk_gt_i32 s2, 0x8ff
	v_lshrrev_b32_e32 v137, 2, v213
	s_cbranch_scc1 .LBB0_1362
	s_add_u32 s0, s64, 0x26d00000
	s_addc_u32 s1, s65, 0
	s_add_u32 s10, s64, 0x29100000
	s_mul_hi_i32 s4, s2, 0x2aaaaaab
	s_addc_u32 s11, s65, 0
	s_lshr_b32 s5, s4, 31
	s_ashr_i32 s4, s4, 1
	s_add_i32 s4, s4, s5
	s_mul_i32 s5, s4, -12
	s_add_i32 s5, s5, s2
	s_lshl_b32 s4, s4, 7
	s_cmpk_lt_i32 s2, 0x600
	s_movk_i32 s12, 0xf800
	s_cselect_b32 s7, s12, 0x7ffff000
	s_movk_i32 s13, 0x800
	s_cselect_b32 s8, s13, 0x1000
	s_and_b32 s7, s7, s4
	s_ashr_i32 s9, s5, 1
	s_sub_i32 s4, s4, s7
	s_and_b32 s14, s9, -2
	s_ashr_i32 s4, s4, 7
	s_lshl_b32 s9, -1, s14
	s_andn2_b32 s9, s4, s9
	s_ashr_i32 s4, s4, s14
	s_lshl_b32 s15, s4, 7
	s_waitcnt vmcnt(0)
	v_lshrrev_b32_e32 v1, 3, v208
	s_waitcnt lgkmcnt(1)
	v_add_u32_e32 v4, 0x200, v208
	v_add_u32_e32 v12, 0x600, v208
	s_sub_i32 s16, s15, 64
	v_lshrrev_b32_e32 v164, 3, v4
	v_or_b32_e32 v165, 0x80, v1
	v_lshrrev_b32_e32 v166, 3, v12
	s_lshr_b32 s8, s8, s14
	v_add_u32_e32 v2, s16, v1
	v_add_u32_e32 v4, s16, v164
	v_add_u32_e32 v10, s16, v165
	v_add_u32_e32 v12, s16, v166
	s_add_i32 s17, s8, -1
	v_max_i32_e32 v2, 0, v2
	v_max_i32_e32 v4, 0, v4
	v_max_i32_e32 v10, 0, v10
	v_max_i32_e32 v12, 0, v12
	v_min_i32_e32 v2, s17, v2
	v_min_i32_e32 v4, s17, v4
	v_min_i32_e32 v10, s17, v10
	v_min_i32_e32 v12, s17, v12
	s_add_i32 s18, s9, s7
	v_lshlrev_b32_e32 v2, s14, v2
	v_lshlrev_b32_e32 v4, s14, v4
	v_lshlrev_b32_e32 v10, s14, v10
	v_lshlrev_b32_e32 v12, s14, v12
	v_add_u32_e32 v2, s18, v2
	s_movk_i32 s20, 0x2c00
	v_mov_b64_e32 v[90:91], s[74:75]
	v_add_u32_e32 v4, s18, v4
	v_add_u32_e32 v10, s18, v10
	v_add_u32_e32 v12, s18, v12
	s_lshr_b32 s6, s6, 2
	s_waitcnt lgkmcnt(0)
; __device__ __forceinline__ void a_prefetch(const bf16* P, int un, int tid, int wave, int fr, int fq, v4u (&vpre)[4], bf16x8& Q0, bf16x8& Q1, bf16x8 (&K)[9][2]) {
;     int s0, sh, r, n, u0, hd; a_decode(un, s0, sh, r, n, u0, hd);
; #pragma unroll
;     for (int i = 0; i < 4; ++i) { const int e = tid + i * NTHREADS, kl = e >> 3, chunk = e & 7; int up = u0 - 64 + kl; up = up < 0 ? 0 : up; up = up > n - 1 ? n - 1 : up;
;         vpre[i] = *(const v4u*)(P + (size_t)(s0 + (up << sh) + r) * DIN + C_VA + hd * 64 + chunk * 8); }
;     { const int u = u0 + 16 * wave + fr; const bf16* qp = P + (size_t)(s0 + (u << sh) + r) * DIN + C_QA + hd * 64 + fq * 8; Q0 = *(const bf16x8*)qp; Q1 = *(const bf16x8*)(qp + 32); }
;     const int ub = u0 + 16 * wave - 64;
; #pragma unroll
;     for (int kt = 0; kt < 9; ++kt) { int up = ub + 16 * kt + fr; up = up < 0 ? 0 : up; up = up > n - 1 ? n - 1 : up;
;         const bf16* kp = P + (size_t)(s0 + (up << sh) + r) * DIN + C_KA + hd * 64 + fq * 8; K[kt][0] = *(const bf16x8*)kp; K[kt][1] = *(const bf16x8*)(kp + 32); }
; }
	v_mad_i64_i32 v[2:3], s[8:9], v2, s20, v[90:91]
	v_mad_i64_i32 v[4:5], s[8:9], v4, s20, v[90:91]
	v_mad_i64_i32 v[10:11], s[8:9], v10, s20, v[90:91]
	v_mad_i64_i32 v[12:13], s[8:9], v12, s20, v[90:91]
	s_and_b32 s21, s6, 0x3ffffff0
	s_add_i32 s8, s21, s15
	v_or_b32_e32 v18, s8, v213
	v_lshlrev_b32_e32 v18, s14, v18
	v_add_u32_e32 v18, s18, v18
	v_mad_i64_i32 v[18:19], s[6:7], v18, s20, v[90:91]
	s_sub_i32 s6, s8, 64
	s_nop 0
	v_or_b32_e32 v92, s6, v213
	v_max_i32_e32 v26, 0, v92
	v_add_u32_e32 v34, 16, v92
	v_add_u32_e32 v42, 32, v92
	v_add_u32_e32 v50, 48, v92
	v_add_u32_e32 v58, 64, v92
	v_add_u32_e32 v66, 0x50, v92
	v_add_u32_e32 v74, 0x60, v92
	v_add_u32_e32 v82, 0x70, v92
	v_add_u32_e32 v92, 0x80, v92
	v_max_i32_e32 v34, 0, v34
	v_max_i32_e32 v42, 0, v42
	v_max_i32_e32 v50, 0, v50
	v_max_i32_e32 v58, 0, v58
	v_max_i32_e32 v66, 0, v66
	v_max_i32_e32 v74, 0, v74
	v_max_i32_e32 v82, 0, v82
	v_max_i32_e32 v92, 0, v92
	s_lshl_b32 s4, s5, 6
	v_min_i32_e32 v26, s17, v26
	v_min_i32_e32 v34, s17, v34
	v_min_i32_e32 v42, s17, v42
	v_min_i32_e32 v50, s17, v50
	v_min_i32_e32 v58, s17, v58
	v_min_i32_e32 v66, s17, v66
	v_min_i32_e32 v74, s17, v74
	v_min_i32_e32 v82, s17, v82
	v_min_i32_e32 v92, s17, v92
	s_ashr_i32 s5, s4, 31
	v_lshlrev_b32_e32 v101, 3, v208
	v_lshlrev_b32_e32 v26, s14, v26
	v_lshlrev_b32_e32 v34, s14, v34
	v_lshlrev_b32_e32 v42, s14, v42
	v_lshlrev_b32_e32 v50, s14, v50
	v_lshlrev_b32_e32 v58, s14, v58
	v_lshlrev_b32_e32 v66, s14, v66
	v_lshlrev_b32_e32 v74, s14, v74
	v_lshlrev_b32_e32 v82, s14, v82
	v_lshlrev_b32_e32 v92, s14, v92
	v_and_b32_e32 v98, 56, v101
	s_lshl_b64 s[4:5], s[4:5], 1
	v_add_u32_e32 v26, s18, v26
	v_add_u32_e32 v34, s18, v34
	v_add_u32_e32 v42, s18, v42
	v_add_u32_e32 v50, s18, v50
	v_add_u32_e32 v58, s18, v58
	v_add_u32_e32 v66, s18, v66
	v_add_u32_e32 v74, s18, v74
	v_add_u32_e32 v82, s18, v82
	v_add_u32_e32 v92, s18, v92
	v_bfe_u32 v99, v208, 4, 2
	v_mov_b32_e32 v135, 0
	v_lshl_add_u64 v[2:3], v[2:3], 0, s[4:5]
	v_lshlrev_b32_e32 v134, 1, v98
	v_lshl_add_u64 v[4:5], v[4:5], 0, s[4:5]
	v_lshl_add_u64 v[10:11], v[10:11], 0, s[4:5]
	v_lshl_add_u64 v[12:13], v[12:13], 0, s[4:5]
	v_mad_i64_i32 v[26:27], s[6:7], v26, s20, v[90:91]
	v_mad_i64_i32 v[34:35], s[6:7], v34, s20, v[90:91]
	v_mad_i64_i32 v[42:43], s[6:7], v42, s20, v[90:91]
	v_mad_i64_i32 v[50:51], s[6:7], v50, s20, v[90:91]
	v_mad_i64_i32 v[58:59], s[6:7], v58, s20, v[90:91]
	v_mad_i64_i32 v[66:67], s[6:7], v66, s20, v[90:91]
	v_mad_i64_i32 v[74:75], s[6:7], v74, s20, v[90:91]
	v_mad_i64_i32 v[82:83], s[6:7], v82, s20, v[90:91]
	v_mad_i64_i32 v[90:91], s[6:7], v92, s20, v[90:91]
	v_lshl_add_u64 v[2:3], v[2:3], 0, v[134:135]
	v_lshl_add_u64 v[6:7], v[4:5], 0, v[134:135]
	v_lshl_add_u64 v[10:11], v[10:11], 0, v[134:135]
	v_lshl_add_u64 v[14:15], v[12:13], 0, v[134:135]
	v_lshl_add_u64 v[18:19], v[18:19], 0, s[4:5]
	v_lshlrev_b32_e32 v134, 4, v99
	v_lshl_add_u64 v[26:27], v[26:27], 0, s[4:5]
	v_lshl_add_u64 v[34:35], v[34:35], 0, s[4:5]
	v_lshl_add_u64 v[42:43], v[42:43], 0, s[4:5]
	v_lshl_add_u64 v[50:51], v[50:51], 0, s[4:5]
	v_lshl_add_u64 v[58:59], v[58:59], 0, s[4:5]
	v_lshl_add_u64 v[66:67], v[66:67], 0, s[4:5]
	v_lshl_add_u64 v[74:75], v[74:75], 0, s[4:5]
	v_lshl_add_u64 v[82:83], v[82:83], 0, s[4:5]
	v_lshl_add_u64 v[90:91], v[90:91], 0, s[4:5]
	v_lshl_add_u64 v[22:23], v[18:19], 0, v[134:135]
	v_lshl_add_u64 v[30:31], v[26:27], 0, v[134:135]
	v_lshl_add_u64 v[38:39], v[34:35], 0, v[134:135]
	v_lshl_add_u64 v[46:47], v[42:43], 0, v[134:135]
	v_lshl_add_u64 v[54:55], v[50:51], 0, v[134:135]
	v_lshl_add_u64 v[62:63], v[58:59], 0, v[134:135]
	v_lshl_add_u64 v[70:71], v[66:67], 0, v[134:135]
	v_lshl_add_u64 v[78:79], v[74:75], 0, v[134:135]
	v_lshl_add_u64 v[86:87], v[82:83], 0, v[134:135]
	v_lshl_add_u64 v[94:95], v[90:91], 0, v[134:135]
	v_and_b32_e32 v239, 15, v208
	v_lshrrev_b32_e32 v255, 6, v208
	v_lshl_or_b32 v239, v255, 4, v239
	v_mul_u32_u24_e32 v239, 0xa0, v239
	v_bfe_u32 v255, v208, 4, 2
	v_lshl_add_u32 v239, v255, 4, v239
	global_load_dwordx4 v[240:243], v[2:3], off offset:1536
	global_load_dwordx4 v[244:247], v[6:7], off offset:1536
	global_load_dwordx4 v[248:251], v[10:11], off offset:1536
	global_load_dwordx4 v[252:255], v[14:15], off offset:1536
	global_load_dwordx4 v[2:5], v[2:3], off offset:3072
	s_nop 0
	global_load_dwordx4 v[6:9], v[6:7], off offset:3072
	s_nop 0
	global_load_dwordx4 v[10:13], v[10:11], off offset:3072
	s_nop 0
	global_load_dwordx4 v[14:17], v[14:15], off offset:3072
	s_nop 0
	global_load_dwordx4 v[18:21], v[22:23], off
	s_nop 0
	global_load_dwordx4 v[22:25], v[22:23], off offset:64
	v_lshlrev_b32_e32 v136, 2, v99
	v_sub_u32_e32 v106, v136, v213
	v_sub_u32_e32 v107, 0, v106
	v_max_i32_e32 v106, v106, v107
	v_or_b32_e32 v168, 0xffffffc0, v136
	v_cvt_f32_u32_e32 v139, v106
	v_or_b32_e32 v169, 0xffffffd0, v136
	v_sub_u32_e32 v106, v213, v168
	s_movk_i32 s23, 0x41
	v_or_b32_e32 v170, 0xffffffe0, v136
	v_cmp_gt_u32_e64 s[6:7], s23, v106
	v_cvt_f32_ubyte0_e32 v141, v106
	v_sub_u32_e32 v106, v213, v169
	v_or_b32_e32 v171, -16, v136
	v_cvt_f32_ubyte0_e32 v143, v106
	v_sub_u32_e32 v106, v213, v170
	v_or_b32_e32 v172, 16, v136
	v_cvt_f32_ubyte0_e32 v145, v106
	v_sub_u32_e32 v106, v213, v171
	v_or_b32_e32 v173, 32, v136
	v_cvt_f32_ubyte0_e32 v147, v106
	v_sub_u32_e32 v106, v172, v213
	v_lshlrev_b32_e32 v102, 4, v208
	v_or3_b32 v103, v137, v136, s21
	s_movk_i32 s4, 0xa0
	v_or_b32_e32 v174, 48, v136
	v_cvt_f32_ubyte0_e32 v149, v106
	v_sub_u32_e32 v106, v173, v213
	v_and_b32_e32 v102, 0x70, v102
	v_mul_lo_u32 v103, v103, s4
	v_or_b32_e32 v175, 64, v136
	v_cvt_f32_ubyte0_e32 v151, v106
	v_sub_u32_e32 v106, v174, v213
	v_lshlrev_b32_e32 v100, 3, v99
	v_add_u32_e32 v102, 0, v102
	v_add_u32_e32 v103, 0, v103
	v_and_b32_e32 v101, 24, v101
	v_cmp_eq_u32_e64 s[4:5], 0, v99
	v_mul_u32_u24_e32 v99, 0xa0, v1
	v_mul_u32_u24_e32 v104, 0xa0, v164
	v_mul_u32_u24_e32 v105, 0xa0, v166
	v_cvt_f32_ubyte0_e32 v153, v106
	v_sub_u32_e32 v106, v175, v213
	v_lshlrev_b32_e32 v158, 1, v98
	v_mbcnt_lo_u32_b32 v98, -1, 0
	s_movk_i32 s22, 0x600
	v_or_b32_e32 v167, 0xffffffc0, v213
	v_cmp_gt_u32_e64 s[8:9], s23, v106
	v_cvt_f32_ubyte0_e32 v155, v106
	v_mov_b32_e32 v156, 0x3e38aa3b
	v_mov_b32_e32 v154, 0x3e38aa3b
	v_mov_b32_e32 v152, 0x3e38aa3b
	v_mov_b32_e32 v150, 0x3e38aa3b
	v_mov_b32_e32 v148, 0x3e38aa3b
	v_mov_b32_e32 v138, 0x3e38aa3b
	v_mov_b32_e32 v146, 0x3e38aa3b
	v_mov_b32_e32 v144, 0x3e38aa3b
	v_mov_b32_e32 v142, 0x3e38aa3b
	v_mov_b32_e32 v140, 0x3e38aa3b
	s_lshl_b32 s24, s68, 6
	s_lshl_b32 s25, s2, 6
	s_mov_b32 s26, 0x41400000
	s_mov_b32 s27, 0xc2fc0000
	v_add_u32_e32 v176, v102, v99
	v_add_u32_e32 v177, v102, v104
	v_add_u32_e32 v178, v102, v105
	v_lshlrev_b32_e32 v160, 1, v100
	s_mov_b32 s29, 0xf149f2ca
	v_mbcnt_hi_u32_b32 v179, -1, v98
	v_add_u32_e32 v180, v103, v101
	v_mov_b32_e32 v181, 0x42800000
	v_mov_b32_e32 v182, 0xf149f2ca
	s_mov_b32 s33, s2
	s_waitcnt vmcnt(0)
	s_branch .LBB0_1358

; #define LAS __attribute__((address_space(3)))
; __device__ __forceinline__ void mixA_mfma(const bf16* P, bf16* OG, float* LSE, LAS unsigned char* lds, int bid, int G, int tid) {
;     ...
;     for (int un = bid; un < NU; un += G) {
;         int s0, sh, r, n, u0, hd; a_decode(un, s0, sh, r, n, u0, hd);
;         const float slope = exp2f(-8.0f * (float)(hd + 1) / 12.0f) * (float)(1 << sh) * L2E;
;         __syncthreads();
; #pragma unroll
;         for (int i = 0; i < 4; ++i) { const int e = tid + i * NTHREADS; *(LAS v4u*)(Vs + (e >> 3) * VROW + (e & 7) * 16) = vpre[i]; }
;         __syncthreads();
;         const int u = u0 + 16 * wave + fr;
;         const size_t qrow = (size_t)(s0 + (u << sh) + r);
;         f32x4 S[10];
;         const int ub = u0 + 16 * wave - 64;
; #pragma unroll
;         for (int kt = 0; kt < 9; ++kt) { f32x4 z = {0.f, 0.f, 0.f, 0.f};
;             z = __builtin_amdgcn_mfma_f32_16x16x32_bf16(Kn[kt][0], Qn0, z, 0, 0, 0);
;             S[kt] = __builtin_amdgcn_mfma_f32_16x16x32_bf16(Kn[kt][1], Qn1, z, 0, 0, 0); }
.LBB0_1358:
	s_mul_hi_i32 s14, s33, 0x2aaaaaab
	s_lshr_b32 s15, s14, 31
	s_ashr_i32 s14, s14, 1
	s_waitcnt vmcnt(5)
	s_barrier
	ds_write_b128 v176, v[2:5]
	ds_write_b128 v177, v[6:9]
	ds_write_b128 v176, v[10:13] offset:20480
	ds_write_b128 v178, v[14:17]
	ds_write_b128 v176, v[240:243] offset:40960
	ds_write_b128 v177, v[244:247] offset:40960
	ds_write_b128 v176, v[248:251] offset:61440
	ds_write_b128 v178, v[252:255] offset:40960
	s_waitcnt lgkmcnt(0)
	s_barrier
	ds_read_b128 v[26:29], v239 offset:40960
	ds_read_b128 v[30:33], v239 offset:41024
	ds_read_b128 v[34:37], v239 offset:43520
	ds_read_b128 v[38:41], v239 offset:43584
	ds_read_b128 v[42:45], v239 offset:46080
	ds_read_b128 v[46:49], v239 offset:46144
	ds_read_b128 v[50:53], v239 offset:48640
	ds_read_b128 v[54:57], v239 offset:48704
	ds_read_b128 v[58:61], v239 offset:51200
	ds_read_b128 v[62:65], v239 offset:51264
	ds_read_b128 v[66:69], v239 offset:53760
	ds_read_b128 v[70:73], v239 offset:53824
	ds_read_b128 v[74:77], v239 offset:56320
	ds_read_b128 v[78:81], v239 offset:56384
	s_waitcnt lgkmcnt(13)
	v_mfma_f32_16x16x32_bf16 v[98:101], v[26:29], v[18:21], 0
	s_add_i32 s15, s14, s15
	s_mul_i32 s14, s15, -12
	s_add_i32 s14, s33, s14
	s_add_i32 s16, s14, 1
	s_waitcnt lgkmcnt(12)
	v_mfma_f32_16x16x32_bf16 v[130:133], v[30:33], v[22:25], v[98:101]
	v_cvt_f32_i32_e32 v102, s16
	s_waitcnt lgkmcnt(11)
	v_mfma_f32_16x16x32_bf16 v[98:101], v[34:37], v[18:21], 0
	v_mul_f32_e32 v102, 0xc1000000, v102
	v_div_scale_f32 v103, s[16:17], s26, s26, v102
	s_waitcnt lgkmcnt(10)
	v_mfma_f32_16x16x32_bf16 v[126:129], v[38:41], v[22:25], v[98:101]
	v_rcp_f32_e32 v104, v103
	ds_read_b128 v[82:85], v239 offset:58880
	ds_read_b128 v[86:89], v239 offset:58944
	ds_read_b128 v[90:93], v239 offset:61440
	ds_read_b128 v[94:97], v239 offset:61504
	s_waitcnt lgkmcnt(13)
	v_mfma_f32_16x16x32_bf16 v[98:101], v[42:45], v[18:21], 0
	v_fma_f32 v105, -v103, v104, 1.0
	v_fmac_f32_e32 v104, v105, v104
	v_div_scale_f32 v105, vcc, v102, s26, v102
	s_waitcnt lgkmcnt(12)
	v_mfma_f32_16x16x32_bf16 v[122:125], v[46:49], v[22:25], v[98:101]
	v_mul_f32_e32 v106, v105, v104
	v_fma_f32 v107, -v103, v106, v105
	v_fmac_f32_e32 v106, v107, v104
	s_waitcnt lgkmcnt(11)
	v_mfma_f32_16x16x32_bf16 v[98:101], v[50:53], v[18:21], 0
	v_fma_f32 v103, -v103, v106, v105
	s_waitcnt lgkmcnt(10)
	v_mfma_f32_16x16x32_bf16 v[118:121], v[54:57], v[22:25], v[98:101]
	s_waitcnt lgkmcnt(9)
	v_mfma_f32_16x16x32_bf16 v[98:101], v[58:61], v[18:21], 0
	s_waitcnt lgkmcnt(8)
	v_mfma_f32_16x16x32_bf16 v[114:117], v[62:65], v[22:25], v[98:101]
	s_nop 5
	v_div_fmas_f32 v98, v103, v104, v106
	v_div_fixup_f32 v102, v98, s26, v102
	s_waitcnt lgkmcnt(7)
	v_mfma_f32_16x16x32_bf16 v[98:101], v[66:69], v[18:21], 0
	v_cmp_gt_f32_e32 vcc, s27, v102
	s_and_b64 s[16:17], vcc, exec
	s_cselect_b32 s16, 0xffffffc0, 0
	s_waitcnt lgkmcnt(6)
	v_mfma_f32_16x16x32_bf16 v[110:113], v[70:73], v[22:25], v[98:101]
	v_cndmask_b32_e32 v103, 0, v181, vcc
	v_add_f32_e32 v102, v102, v103
	v_exp_f32_e32 v102, v102
	s_waitcnt lgkmcnt(5)
	v_mfma_f32_16x16x32_bf16 v[98:101], v[74:77], v[18:21], 0
	s_add_i32 s31, s33, s68
	s_cmpk_gt_i32 s31, 0x8ff
	v_ldexp_f32 v134, v102, s16
	s_waitcnt lgkmcnt(4)
	v_mfma_f32_16x16x32_bf16 v[106:109], v[78:81], v[22:25], v[98:101]
	s_cselect_b64 s[16:17], -1, 0
	s_and_b64 vcc, exec, s[16:17]
	s_waitcnt lgkmcnt(3)
	v_mfma_f32_16x16x32_bf16 v[98:101], v[82:85], v[18:21], 0
	s_waitcnt lgkmcnt(2)
	v_mfma_f32_16x16x32_bf16 v[102:105], v[86:89], v[22:25], v[98:101]
	s_waitcnt lgkmcnt(1)
	v_mfma_f32_16x16x32_bf16 v[98:101], v[90:93], v[18:21], 0
	s_waitcnt lgkmcnt(0)
	v_mfma_f32_16x16x32_bf16 v[98:101], v[94:97], v[22:25], v[98:101]
	s_cbranch_vccnz .LBB0_1360
; __device__ __forceinline__ void a_prefetch(const bf16* P, int un, int tid, int wave, int fr, int fq, v4u (&vpre)[4], bf16x8& Q0, bf16x8& Q1, bf16x8 (&K)[9][2]) {
;     int s0, sh, r, n, u0, hd; a_decode(un, s0, sh, r, n, u0, hd);
; #pragma unroll
;     for (int i = 0; i < 4; ++i) { const int e = tid + i * NTHREADS, kl = e >> 3, chunk = e & 7; int up = u0 - 64 + kl; up = up < 0 ? 0 : up; up = up > n - 1 ? n - 1 : up;
;         vpre[i] = *(const v4u*)(P + (size_t)(s0 + (up << sh) + r) * DIN + C_VA + hd * 64 + chunk * 8); }
;     { const int u = u0 + 16 * wave + fr; const bf16* qp = P + (size_t)(s0 + (u << sh) + r) * DIN + C_QA + hd * 64 + fq * 8; Q0 = *(const bf16x8*)qp; Q1 = *(const bf16x8*)(qp + 32); }
;     const int ub = u0 + 16 * wave - 64;
; #pragma unroll
;     for (int kt = 0; kt < 9; ++kt) { int up = ub + 16 * kt + fr; up = up < 0 ? 0 : up; up = up > n - 1 ? n - 1 : up;
;         const bf16* kp = P + (size_t)(s0 + (up << sh) + r) * DIN + C_KA + hd * 64 + fq * 8; K[kt][0] = *(const bf16x8*)kp; K[kt][1] = *(const bf16x8*)(kp + 32); }
; }
	s_mul_hi_i32 s18, s31, 0x2aaaaaab
	s_lshr_b32 s19, s18, 31
	s_ashr_i32 s18, s18, 1
	s_add_i32 s18, s18, s19
	s_mul_i32 s19, s18, -12
	s_add_i32 s19, s31, s19
	s_lshl_b32 s35, s18, 7
	s_cmpk_lt_i32 s31, 0x600
	s_cselect_b32 s40, s12, 0x7ffff000
	s_cselect_b32 s41, s13, 0x1000
	s_and_b32 s40, s40, s35
	s_ashr_i32 s19, s19, 1
	s_sub_i32 s35, s35, s40
	s_and_b32 s42, s19, -2
	s_ashr_i32 s35, s35, 7
	s_lshl_b32 s19, -1, s42
	s_andn2_b32 s19, s35, s19
	s_ashr_i32 s35, s35, s42
	s_lshl_b32 s35, s35, 7
	s_sub_i32 s43, s35, 64
	s_add_i32 s35, s35, s21
	v_add_u32_e32 v92, s35, v167
	s_lshr_b32 s41, s41, s42
	v_add_u32_e32 v2, s43, v1
	v_add_u32_e32 v4, s43, v164
	v_add_u32_e32 v10, s43, v165
	v_add_u32_e32 v12, s43, v166
	v_max_i32_e32 v26, 0, v92
	v_add_u32_e32 v34, 16, v92
	v_add_u32_e32 v42, 32, v92
	v_add_u32_e32 v50, 48, v92
	v_add_u32_e32 v58, 64, v92
	v_add_u32_e32 v66, 0x50, v92
	v_add_u32_e32 v74, 0x60, v92
	v_add_u32_e32 v82, 0x70, v92
	v_add_u32_e32 v92, 0x80, v92
	s_add_i32 s50, s41, -1
	v_max_i32_e32 v2, 0, v2
	v_max_i32_e32 v4, 0, v4
	v_max_i32_e32 v10, 0, v10
	v_max_i32_e32 v12, 0, v12
	v_max_i32_e32 v34, 0, v34
	v_max_i32_e32 v42, 0, v42
	v_max_i32_e32 v50, 0, v50
	v_max_i32_e32 v58, 0, v58
	v_max_i32_e32 v66, 0, v66
	v_max_i32_e32 v74, 0, v74
	v_max_i32_e32 v82, 0, v82
	v_max_i32_e32 v92, 0, v92
	s_add_i32 s51, s19, s40
	s_mulk_i32 s18, 0xfd00
	s_add_i32 s19, s24, s25
	v_min_i32_e32 v2, s50, v2
	v_min_i32_e32 v4, s50, v4
	v_min_i32_e32 v10, s50, v10
	v_min_i32_e32 v12, s50, v12
	v_or_b32_e32 v18, s35, v213
	v_min_i32_e32 v26, s50, v26
	v_min_i32_e32 v34, s50, v34
	v_min_i32_e32 v42, s50, v42
	v_min_i32_e32 v50, s50, v50
	v_min_i32_e32 v58, s50, v58
	v_min_i32_e32 v66, s50, v66
	v_min_i32_e32 v74, s50, v74
	v_min_i32_e32 v82, s50, v82
	v_min_i32_e32 v92, s50, v92
	s_add_i32 s18, s19, s18
	v_lshlrev_b32_e32 v2, s42, v2
	v_lshlrev_b32_e32 v4, s42, v4
	v_lshlrev_b32_e32 v10, s42, v10
	v_lshlrev_b32_e32 v12, s42, v12
	v_lshlrev_b32_e32 v18, s42, v18
	v_lshlrev_b32_e32 v26, s42, v26
	v_lshlrev_b32_e32 v34, s42, v34
	v_lshlrev_b32_e32 v42, s42, v42
	v_lshlrev_b32_e32 v50, s42, v50
	v_lshlrev_b32_e32 v58, s42, v58
	v_lshlrev_b32_e32 v66, s42, v66
	v_lshlrev_b32_e32 v74, s42, v74
	v_lshlrev_b32_e32 v82, s42, v82
	v_lshlrev_b32_e32 v92, s42, v92
	s_ashr_i32 s19, s18, 31
	v_add_u32_e32 v2, s51, v2
	v_mov_b64_e32 v[90:91], s[74:75]
	v_add_u32_e32 v4, s51, v4
	v_add_u32_e32 v10, s51, v10
	v_add_u32_e32 v12, s51, v12
	v_add_u32_e32 v18, s51, v18
	v_add_u32_e32 v26, s51, v26
	v_add_u32_e32 v34, s51, v34
	v_add_u32_e32 v42, s51, v42
	v_add_u32_e32 v50, s51, v50
	v_add_u32_e32 v58, s51, v58
	v_add_u32_e32 v66, s51, v66
	v_add_u32_e32 v74, s51, v74
	v_add_u32_e32 v82, s51, v82
	v_add_u32_e32 v92, s51, v92
	v_mad_i64_i32 v[2:3], s[40:41], v2, s20, v[90:91]
	s_lshl_b64 s[18:19], s[18:19], 1
	v_mad_i64_i32 v[4:5], s[40:41], v4, s20, v[90:91]
	v_mad_i64_i32 v[10:11], s[40:41], v10, s20, v[90:91]
	v_mad_i64_i32 v[12:13], s[40:41], v12, s20, v[90:91]
	v_mad_i64_i32 v[18:19], s[40:41], v18, s20, v[90:91]
	v_mad_i64_i32 v[26:27], s[40:41], v26, s20, v[90:91]
	v_mad_i64_i32 v[34:35], s[40:41], v34, s20, v[90:91]
	v_mad_i64_i32 v[42:43], s[40:41], v42, s20, v[90:91]
	v_mad_i64_i32 v[50:51], s[40:41], v50, s20, v[90:91]
	v_mad_i64_i32 v[58:59], s[40:41], v58, s20, v[90:91]
	v_mad_i64_i32 v[66:67], s[40:41], v66, s20, v[90:91]
	v_mad_i64_i32 v[74:75], s[40:41], v74, s20, v[90:91]
	v_mad_i64_i32 v[82:83], s[40:41], v82, s20, v[90:91]
	v_mad_i64_i32 v[90:91], s[40:41], v92, s20, v[90:91]
	v_lshl_add_u64 v[2:3], v[2:3], 0, s[18:19]
	v_mov_b32_e32 v159, v135
	v_lshl_add_u64 v[4:5], v[4:5], 0, s[18:19]
	v_lshl_add_u64 v[10:11], v[10:11], 0, s[18:19]
	v_lshl_add_u64 v[12:13], v[12:13], 0, s[18:19]
	v_lshl_add_u64 v[18:19], v[18:19], 0, s[18:19]
	v_mov_b32_e32 v161, v135
	v_lshl_add_u64 v[26:27], v[26:27], 0, s[18:19]
	v_lshl_add_u64 v[34:35], v[34:35], 0, s[18:19]
	v_lshl_add_u64 v[42:43], v[42:43], 0, s[18:19]
	v_lshl_add_u64 v[50:51], v[50:51], 0, s[18:19]
	v_lshl_add_u64 v[58:59], v[58:59], 0, s[18:19]
	v_lshl_add_u64 v[66:67], v[66:67], 0, s[18:19]
	v_lshl_add_u64 v[74:75], v[74:75], 0, s[18:19]
	v_lshl_add_u64 v[82:83], v[82:83], 0, s[18:19]
	v_lshl_add_u64 v[90:91], v[90:91], 0, s[18:19]
	v_lshl_add_u64 v[2:3], v[2:3], 0, v[158:159]
	v_lshl_add_u64 v[6:7], v[4:5], 0, v[158:159]
	v_lshl_add_u64 v[10:11], v[10:11], 0, v[158:159]
	v_lshl_add_u64 v[14:15], v[12:13], 0, v[158:159]
	v_lshl_add_u64 v[22:23], v[18:19], 0, v[160:161]
	v_lshl_add_u64 v[30:31], v[26:27], 0, v[160:161]
	v_lshl_add_u64 v[38:39], v[34:35], 0, v[160:161]
	v_lshl_add_u64 v[46:47], v[42:43], 0, v[160:161]
	v_lshl_add_u64 v[54:55], v[50:51], 0, v[160:161]
	v_lshl_add_u64 v[62:63], v[58:59], 0, v[160:161]
	v_lshl_add_u64 v[70:71], v[66:67], 0, v[160:161]
	v_lshl_add_u64 v[78:79], v[74:75], 0, v[160:161]
	v_lshl_add_u64 v[86:87], v[82:83], 0, v[160:161]
	v_lshl_add_u64 v[94:95], v[90:91], 0, v[160:161]
	global_load_dwordx4 v[240:243], v[2:3], off offset:1536
	global_load_dwordx4 v[244:247], v[6:7], off offset:1536
	global_load_dwordx4 v[248:251], v[10:11], off offset:1536
	global_load_dwordx4 v[252:255], v[14:15], off offset:1536
	global_load_dwordx4 v[2:5], v[2:3], off offset:3072
	s_nop 0
	global_load_dwordx4 v[6:9], v[6:7], off offset:3072
	s_nop 0
	global_load_dwordx4 v[10:13], v[10:11], off offset:3072
	s_nop 0
	global_load_dwordx4 v[14:17], v[14:15], off offset:3072
	s_nop 0
	global_load_dwordx4 v[18:21], v[22:23], off
	s_nop 0
	global_load_dwordx4 v[22:25], v[22:23], off offset:64
